# nine split barriers; arrive sites without the trailing workgroup barrier (other waves start the transpose slice while thread 0 signals) and no store drain before the wait
# baseline (speedup 1.0000x reference)
.Lsl0_out:
	s_cmp_gt_i32 s88, 0
	s_cbranch_scc1 .Lsb0_skip
	s_cmp_lt_i32 s89, 2
	s_cbranch_scc1 .Lsb0_skip
	s_waitcnt lgkmcnt(0)
	s_and_saveexec_b64 s[16:17], s[92:93]
	s_cbranch_execz .Lsb0_done
	v_mov_b32_e32 v0, 0x24008
	ds_read_b32 v1, v0
	buffer_inv sc1
	s_add_u32 s18, s34, 0xed10500
	s_addc_u32 s19, s35, 0
	v_mov_b32_e32 v0, 0
	s_mov_b32 s20, 0
	s_waitcnt lgkmcnt(0)

.LBB0_188:
	s_or_b64 exec, exec, s[6:7]
	s_waitcnt lgkmcnt(0)
.LBB0_189:
	s_cmp_lg_u32 s88, 0
	s_cbranch_scc1 .Lsl1_out
	s_cmp_lg_u32 s89, 18
	s_cbranch_scc1 .Lsl1_out
	s_load_dword s4, s[0:1], 0x120
	s_load_dwordx16 s[52:67], s[0:1], 0x0
	s_load_dwordx16 s[68:83], s[0:1], 0x80
	s_waitcnt lgkmcnt(0)
	s_lshl_b32 s4, s4, 1
	s_mul_i32 s5, s4, 3
	s_lshl_b32 s33, s2, 1
	s_add_i32 s33, s33, s5
	s_mov_b32 s5, 4
	s_mul_i32 s4, s4, s5
	s_min_u32 s4, s4, 0x15d0
	s_cmp_ge_i32 s33, s4
	s_cbranch_scc1 .Lsl1_out
	s_add_u32 s94, s34, 0x1da0000
	s_addc_u32 s95, s35, 0
	v_writelane_b32 v252, s90, 0
	s_add_u32 s4, s34, 0x7a0000
	s_addc_u32 s5, s35, 0
	v_writelane_b32 v252, s91, 1
	v_writelane_b32 v252, s4, 2
	v_lshrrev_b32_e32 v138, 8, v204
	v_and_b32_e32 v139, 0xff, v204
	v_writelane_b32 v252, s5, 3
	s_add_u32 s4, s34, 0x720000
	s_addc_u32 s5, s35, 0
	v_writelane_b32 v252, s4, 4
	v_mul_u32_u24_e32 v140, 0x12000, v138
	v_mov_b32_e32 v129, 0
	v_writelane_b32 v252, s5, 5
	s_add_u32 s4, s34, 0x520000
	s_addc_u32 s5, s35, 0
	s_add_u32 s90, s34, 0x4a0000
	s_addc_u32 s91, s35, 0
	s_add_u32 s96, s34, 0x440000
	s_addc_u32 s97, s35, 0
	s_add_u32 s16, s34, 0x28a0000
	s_addc_u32 s17, s35, 0
	s_add_u32 s18, s0, 0x120
	v_writelane_b32 v252, s4, 6
	s_addc_u32 s19, s1, 0
	s_movk_i32 s8, 0x104
	s_movk_i32 s9, 0xffe0
	s_movk_i32 s10, 0x6000
	s_movk_i32 s11, 0x400
	s_mov_b32 s12, 0xbfb8aa3b
	s_mov_b32 s13, 0x42ce8ed0
	s_mov_b32 s14, 0xc2b17218
	s_movk_i32 s15, 0x1800
	v_mov_b32_e32 v141, 0xfffffd40
	v_mov_b32_e32 v142, 0xb00000
	v_mov_b32_e32 v143, 0x580000
	v_mov_b32_e32 v144, 0x7f800000
	v_writelane_b32 v252, s5, 7
	s_branch .Lsl1_22

.Lsl1_out:
	s_cmp_gt_i32 s88, 1
	s_cbranch_scc1 .Lsb1_skip
	s_cmp_lt_i32 s89, 3
	s_cbranch_scc1 .Lsb1_skip
	s_waitcnt lgkmcnt(0)
	s_and_saveexec_b64 s[16:17], s[92:93]
	s_cbranch_execz .Lsb1_done
	v_mov_b32_e32 v0, 0x24008
	ds_read_b32 v1, v0
	buffer_inv sc1
	s_add_u32 s18, s34, 0xed10500
	s_addc_u32 s19, s35, 0
	v_mov_b32_e32 v0, 0
	s_mov_b32 s20, 0
	s_waitcnt lgkmcnt(0)

.LBB0_479:
	s_or_b64 exec, exec, s[6:7]
	s_waitcnt lgkmcnt(0)
.LBB0_480:
	s_cmp_lg_u32 s88, 0
	s_cbranch_scc1 .Lsl2_out
	s_cmp_lg_u32 s89, 18
	s_cbranch_scc1 .Lsl2_out
	s_load_dword s4, s[0:1], 0x120
	s_load_dwordx16 s[52:67], s[0:1], 0x0
	s_load_dwordx16 s[68:83], s[0:1], 0x80
	s_waitcnt lgkmcnt(0)
	s_lshl_b32 s4, s4, 1
	s_mul_i32 s5, s4, 4
	s_lshl_b32 s33, s2, 1
	s_add_i32 s33, s33, s5
	s_mov_b32 s5, 5
	s_mul_i32 s4, s4, s5
	s_min_u32 s4, s4, 0x15d0
	s_cmp_ge_i32 s33, s4
	s_cbranch_scc1 .Lsl2_out
	s_add_u32 s94, s34, 0x1da0000
	s_addc_u32 s95, s35, 0
	v_writelane_b32 v252, s90, 0
	s_add_u32 s4, s34, 0x7a0000
	s_addc_u32 s5, s35, 0
	v_writelane_b32 v252, s91, 1
	v_writelane_b32 v252, s4, 2
	v_lshrrev_b32_e32 v138, 8, v204
	v_and_b32_e32 v139, 0xff, v204
	v_writelane_b32 v252, s5, 3
	s_add_u32 s4, s34, 0x720000
	s_addc_u32 s5, s35, 0
	v_writelane_b32 v252, s4, 4
	v_mul_u32_u24_e32 v140, 0x12000, v138
	v_mov_b32_e32 v129, 0
	v_writelane_b32 v252, s5, 5
	s_add_u32 s4, s34, 0x520000
	s_addc_u32 s5, s35, 0
	s_add_u32 s90, s34, 0x4a0000
	s_addc_u32 s91, s35, 0
	s_add_u32 s96, s34, 0x440000
	s_addc_u32 s97, s35, 0
	s_add_u32 s16, s34, 0x28a0000
	s_addc_u32 s17, s35, 0
	s_add_u32 s18, s0, 0x120
	v_writelane_b32 v252, s4, 6
	s_addc_u32 s19, s1, 0
	s_movk_i32 s8, 0x104
	s_movk_i32 s9, 0xffe0
	s_movk_i32 s10, 0x6000
	s_movk_i32 s11, 0x400
	s_mov_b32 s12, 0xbfb8aa3b
	s_mov_b32 s13, 0x42ce8ed0
	s_mov_b32 s14, 0xc2b17218
	s_movk_i32 s15, 0x1800
	v_mov_b32_e32 v141, 0xfffffd40
	v_mov_b32_e32 v142, 0xb00000
	v_mov_b32_e32 v143, 0x580000
	v_mov_b32_e32 v144, 0x7f800000
	v_writelane_b32 v252, s5, 7
	s_branch .Lsl2_22

.Lsl2_out:
	s_cmp_gt_i32 s88, 2
	s_cbranch_scc1 .Lsb2_skip
	s_cmp_lt_i32 s89, 4
	s_cbranch_scc1 .Lsb2_skip
	s_waitcnt lgkmcnt(0)
	s_and_saveexec_b64 s[16:17], s[92:93]
	s_cbranch_execz .Lsb2_done
	v_mov_b32_e32 v0, 0x24008
	ds_read_b32 v1, v0
	buffer_inv sc1
	s_add_u32 s18, s34, 0xed10500
	s_addc_u32 s19, s35, 0
	v_mov_b32_e32 v0, 0
	s_mov_b32 s20, 0
	s_waitcnt lgkmcnt(0)

.LBB0_614:
	s_or_b64 exec, exec, s[6:7]
	s_waitcnt lgkmcnt(0)
.LBB0_615:
	s_cmp_lg_u32 s88, 0
	s_cbranch_scc1 .Lsl3_out
	s_cmp_lg_u32 s89, 18
	s_cbranch_scc1 .Lsl3_out
	s_load_dword s4, s[0:1], 0x120
	s_load_dwordx16 s[52:67], s[0:1], 0x0
	s_load_dwordx16 s[68:83], s[0:1], 0x80
	s_waitcnt lgkmcnt(0)
	s_lshl_b32 s4, s4, 1
	s_mul_i32 s5, s4, 5
	s_lshl_b32 s33, s2, 1
	s_add_i32 s33, s33, s5
	s_mov_b32 s5, 6
	s_mul_i32 s4, s4, s5
	s_min_u32 s4, s4, 0x15d0
	s_cmp_ge_i32 s33, s4
	s_cbranch_scc1 .Lsl3_out
	s_add_u32 s94, s34, 0x1da0000
	s_addc_u32 s95, s35, 0
	v_writelane_b32 v252, s90, 0
	s_add_u32 s4, s34, 0x7a0000
	s_addc_u32 s5, s35, 0
	v_writelane_b32 v252, s91, 1
	v_writelane_b32 v252, s4, 2
	v_lshrrev_b32_e32 v138, 8, v204
	v_and_b32_e32 v139, 0xff, v204
	v_writelane_b32 v252, s5, 3
	s_add_u32 s4, s34, 0x720000
	s_addc_u32 s5, s35, 0
	v_writelane_b32 v252, s4, 4
	v_mul_u32_u24_e32 v140, 0x12000, v138
	v_mov_b32_e32 v129, 0
	v_writelane_b32 v252, s5, 5
	s_add_u32 s4, s34, 0x520000
	s_addc_u32 s5, s35, 0
	s_add_u32 s90, s34, 0x4a0000
	s_addc_u32 s91, s35, 0
	s_add_u32 s96, s34, 0x440000
	s_addc_u32 s97, s35, 0
	s_add_u32 s16, s34, 0x28a0000
	s_addc_u32 s17, s35, 0
	s_add_u32 s18, s0, 0x120
	v_writelane_b32 v252, s4, 6
	s_addc_u32 s19, s1, 0
	s_movk_i32 s8, 0x104
	s_movk_i32 s9, 0xffe0
	s_movk_i32 s10, 0x6000
	s_movk_i32 s11, 0x400
	s_mov_b32 s12, 0xbfb8aa3b
	s_mov_b32 s13, 0x42ce8ed0
	s_mov_b32 s14, 0xc2b17218
	s_movk_i32 s15, 0x1800
	v_mov_b32_e32 v141, 0xfffffd40
	v_mov_b32_e32 v142, 0xb00000
	v_mov_b32_e32 v143, 0x580000
	v_mov_b32_e32 v144, 0x7f800000
	v_writelane_b32 v252, s5, 7
	s_branch .Lsl3_22

.Lsl3_out:
	s_cmp_gt_i32 s88, 3
	s_cbranch_scc1 .Lsb3_skip
	s_cmp_lt_i32 s89, 5
	s_cbranch_scc1 .Lsb3_skip
	s_waitcnt lgkmcnt(0)
	s_and_saveexec_b64 s[16:17], s[92:93]
	s_cbranch_execz .Lsb3_done
	v_mov_b32_e32 v0, 0x24008
	ds_read_b32 v1, v0
	buffer_inv sc1
	s_add_u32 s18, s34, 0xed10500
	s_addc_u32 s19, s35, 0
	v_mov_b32_e32 v0, 0
	s_mov_b32 s20, 0
	s_waitcnt lgkmcnt(0)

.LBB0_843:
	s_or_b64 exec, exec, s[6:7]
	s_waitcnt lgkmcnt(0)
.LBB0_844:
	s_cmp_lg_u32 s88, 0
	s_cbranch_scc1 .Lsl4_out
	s_cmp_lg_u32 s89, 18
	s_cbranch_scc1 .Lsl4_out
	s_load_dword s4, s[0:1], 0x120
	s_load_dwordx16 s[52:67], s[0:1], 0x0
	s_load_dwordx16 s[68:83], s[0:1], 0x80
	s_waitcnt lgkmcnt(0)
	s_lshl_b32 s4, s4, 1
	s_mul_i32 s5, s4, 6
	s_lshl_b32 s33, s2, 1
	s_add_i32 s33, s33, s5
	s_mov_b32 s5, 7
	s_mul_i32 s4, s4, s5
	s_min_u32 s4, s4, 0x15d0
	s_cmp_ge_i32 s33, s4
	s_cbranch_scc1 .Lsl4_out
	s_add_u32 s94, s34, 0x1da0000
	s_addc_u32 s95, s35, 0
	v_writelane_b32 v252, s90, 0
	s_add_u32 s4, s34, 0x7a0000
	s_addc_u32 s5, s35, 0
	v_writelane_b32 v252, s91, 1
	v_writelane_b32 v252, s4, 2
	v_lshrrev_b32_e32 v138, 8, v204
	v_and_b32_e32 v139, 0xff, v204
	v_writelane_b32 v252, s5, 3
	s_add_u32 s4, s34, 0x720000
	s_addc_u32 s5, s35, 0
	v_writelane_b32 v252, s4, 4
	v_mul_u32_u24_e32 v140, 0x12000, v138
	v_mov_b32_e32 v129, 0
	v_writelane_b32 v252, s5, 5
	s_add_u32 s4, s34, 0x520000
	s_addc_u32 s5, s35, 0
	s_add_u32 s90, s34, 0x4a0000
	s_addc_u32 s91, s35, 0
	s_add_u32 s96, s34, 0x440000
	s_addc_u32 s97, s35, 0
	s_add_u32 s16, s34, 0x28a0000
	s_addc_u32 s17, s35, 0
	s_add_u32 s18, s0, 0x120
	v_writelane_b32 v252, s4, 6
	s_addc_u32 s19, s1, 0
	s_movk_i32 s8, 0x104
	s_movk_i32 s9, 0xffe0
	s_movk_i32 s10, 0x6000
	s_movk_i32 s11, 0x400
	s_mov_b32 s12, 0xbfb8aa3b
	s_mov_b32 s13, 0x42ce8ed0
	s_mov_b32 s14, 0xc2b17218
	s_movk_i32 s15, 0x1800
	v_mov_b32_e32 v141, 0xfffffd40
	v_mov_b32_e32 v142, 0xb00000
	v_mov_b32_e32 v143, 0x580000
	v_mov_b32_e32 v144, 0x7f800000
	v_writelane_b32 v252, s5, 7
	s_branch .Lsl4_22

.Lsl4_out:
	s_cmp_gt_i32 s88, 4
	s_cbranch_scc1 .Lsb4_skip
	s_cmp_lt_i32 s89, 6
	s_cbranch_scc1 .Lsb4_skip
	s_waitcnt lgkmcnt(0)
	s_and_saveexec_b64 s[16:17], s[92:93]
	s_cbranch_execz .Lsb4_done
	v_mov_b32_e32 v0, 0x24008
	ds_read_b32 v1, v0
	buffer_inv sc1
	s_add_u32 s18, s34, 0xed10500
	s_addc_u32 s19, s35, 0
	v_mov_b32_e32 v0, 0
	s_mov_b32 s20, 0
	s_waitcnt lgkmcnt(0)

.LBB0_1013:
	s_or_b64 exec, exec, s[4:5]
	s_waitcnt lgkmcnt(0)
.LBB0_1014:
	s_cmp_lg_u32 s88, 0
	s_cbranch_scc1 .Lsl6_out
	s_cmp_lg_u32 s89, 18
	s_cbranch_scc1 .Lsl6_out
	s_load_dword s4, s[0:1], 0x120
	s_load_dwordx16 s[52:67], s[0:1], 0x0
	s_load_dwordx16 s[68:83], s[0:1], 0x80
	s_waitcnt lgkmcnt(0)
	s_lshl_b32 s4, s4, 1
	s_mul_i32 s5, s4, 7
	s_lshl_b32 s33, s2, 1
	s_add_i32 s33, s33, s5
	s_mov_b32 s5, 8
	s_mul_i32 s4, s4, s5
	s_min_u32 s4, s4, 0x15d0
	s_cmp_ge_i32 s33, s4
	s_cbranch_scc1 .Lsl6_out
	s_add_u32 s94, s34, 0x1da0000
	s_addc_u32 s95, s35, 0
	v_writelane_b32 v252, s90, 0
	s_add_u32 s4, s34, 0x7a0000
	s_addc_u32 s5, s35, 0
	v_writelane_b32 v252, s91, 1
	v_writelane_b32 v252, s4, 2
	v_lshrrev_b32_e32 v138, 8, v204
	v_and_b32_e32 v139, 0xff, v204
	v_writelane_b32 v252, s5, 3
	s_add_u32 s4, s34, 0x720000
	s_addc_u32 s5, s35, 0
	v_writelane_b32 v252, s4, 4
	v_mul_u32_u24_e32 v140, 0x12000, v138
	v_mov_b32_e32 v129, 0
	v_writelane_b32 v252, s5, 5
	s_add_u32 s4, s34, 0x520000
	s_addc_u32 s5, s35, 0
	s_add_u32 s90, s34, 0x4a0000
	s_addc_u32 s91, s35, 0
	s_add_u32 s96, s34, 0x440000
	s_addc_u32 s97, s35, 0
	s_add_u32 s16, s34, 0x28a0000
	s_addc_u32 s17, s35, 0
	s_add_u32 s18, s0, 0x120
	v_writelane_b32 v252, s4, 6
	s_addc_u32 s19, s1, 0
	s_movk_i32 s8, 0x104
	s_movk_i32 s9, 0xffe0
	s_movk_i32 s10, 0x6000
	s_movk_i32 s11, 0x400
	s_mov_b32 s12, 0xbfb8aa3b
	s_mov_b32 s13, 0x42ce8ed0
	s_mov_b32 s14, 0xc2b17218
	s_movk_i32 s15, 0x1800
	v_mov_b32_e32 v141, 0xfffffd40
	v_mov_b32_e32 v142, 0xb00000
	v_mov_b32_e32 v143, 0x580000
	v_mov_b32_e32 v144, 0x7f800000
	v_writelane_b32 v252, s5, 7
	s_branch .Lsl6_22

.Lsl6_out:
	s_cmp_gt_i32 s88, 6
	s_cbranch_scc1 .Lsb6_skip
	s_cmp_lt_i32 s89, 8
	s_cbranch_scc1 .Lsb6_skip
	s_waitcnt lgkmcnt(0)
	s_and_saveexec_b64 s[16:17], s[92:93]
	s_cbranch_execz .Lsb6_done
	v_mov_b32_e32 v0, 0x24008
	ds_read_b32 v1, v0
	buffer_inv sc1
	s_add_u32 s18, s34, 0xed10500
	s_addc_u32 s19, s35, 0
	v_mov_b32_e32 v0, 0
	s_mov_b32 s20, 0
	s_waitcnt lgkmcnt(0)

.LBB0_1076:
	s_or_b64 exec, exec, s[4:5]
	s_waitcnt lgkmcnt(0)
.LBB0_1077:
	s_cmp_lg_u32 s88, 0
	s_cbranch_scc1 .Lsl7_out
	s_cmp_lg_u32 s89, 18
	s_cbranch_scc1 .Lsl7_out
	s_load_dword s4, s[0:1], 0x120
	s_load_dwordx16 s[52:67], s[0:1], 0x0
	s_load_dwordx16 s[68:83], s[0:1], 0x80
	s_waitcnt lgkmcnt(0)
	s_lshl_b32 s4, s4, 1
	s_mul_i32 s5, s4, 8
	s_lshl_b32 s33, s2, 1
	s_add_i32 s33, s33, s5
	s_mov_b32 s5, 9
	s_mul_i32 s4, s4, s5
	s_min_u32 s4, s4, 0x15d0
	s_cmp_ge_i32 s33, s4
	s_cbranch_scc1 .Lsl7_out
	s_add_u32 s94, s34, 0x1da0000
	s_addc_u32 s95, s35, 0
	v_writelane_b32 v252, s90, 0
	s_add_u32 s4, s34, 0x7a0000
	s_addc_u32 s5, s35, 0
	v_writelane_b32 v252, s91, 1
	v_writelane_b32 v252, s4, 2
	v_lshrrev_b32_e32 v138, 8, v204
	v_and_b32_e32 v139, 0xff, v204
	v_writelane_b32 v252, s5, 3
	s_add_u32 s4, s34, 0x720000
	s_addc_u32 s5, s35, 0
	v_writelane_b32 v252, s4, 4
	v_mul_u32_u24_e32 v140, 0x12000, v138
	v_mov_b32_e32 v129, 0
	v_writelane_b32 v252, s5, 5
	s_add_u32 s4, s34, 0x520000
	s_addc_u32 s5, s35, 0
	s_add_u32 s90, s34, 0x4a0000
	s_addc_u32 s91, s35, 0
	s_add_u32 s96, s34, 0x440000
	s_addc_u32 s97, s35, 0
	s_add_u32 s16, s34, 0x28a0000
	s_addc_u32 s17, s35, 0
	s_add_u32 s18, s0, 0x120
	v_writelane_b32 v252, s4, 6
	s_addc_u32 s19, s1, 0
	s_movk_i32 s8, 0x104
	s_movk_i32 s9, 0xffe0
	s_movk_i32 s10, 0x6000
	s_movk_i32 s11, 0x400
	s_mov_b32 s12, 0xbfb8aa3b
	s_mov_b32 s13, 0x42ce8ed0
	s_mov_b32 s14, 0xc2b17218
	s_movk_i32 s15, 0x1800
	v_mov_b32_e32 v141, 0xfffffd40
	v_mov_b32_e32 v142, 0xb00000
	v_mov_b32_e32 v143, 0x580000
	v_mov_b32_e32 v144, 0x7f800000
	v_writelane_b32 v252, s5, 7
	s_branch .Lsl7_22

.Lsl7_out:
	s_cmp_gt_i32 s88, 7
	s_cbranch_scc1 .Lsb7_skip
	s_cmp_lt_i32 s89, 9
	s_cbranch_scc1 .Lsb7_skip
	s_waitcnt lgkmcnt(0)
	s_and_saveexec_b64 s[16:17], s[92:93]
	s_cbranch_execz .Lsb7_done
	v_mov_b32_e32 v0, 0x24008
	ds_read_b32 v1, v0
	buffer_inv sc1
	s_add_u32 s18, s34, 0xed10500
	s_addc_u32 s19, s35, 0
	v_mov_b32_e32 v0, 0
	s_mov_b32 s20, 0
	s_waitcnt lgkmcnt(0)

.LBB0_1139:
	s_or_b64 exec, exec, s[6:7]
	s_waitcnt lgkmcnt(0)
.LBB0_1140:
	s_cmp_lg_u32 s88, 0
	s_cbranch_scc1 .Lsl8_out
	s_cmp_lg_u32 s89, 18
	s_cbranch_scc1 .Lsl8_out
	s_load_dword s4, s[0:1], 0x120
	s_load_dwordx16 s[52:67], s[0:1], 0x0
	s_load_dwordx16 s[68:83], s[0:1], 0x80
	s_waitcnt lgkmcnt(0)
	s_lshl_b32 s4, s4, 1
	s_mul_i32 s5, s4, 9
	s_lshl_b32 s33, s2, 1
	s_add_i32 s33, s33, s5
	s_mov_b32 s5, 10
	s_mul_i32 s4, s4, s5
	s_min_u32 s4, s4, 0x15d0
	s_cmp_ge_i32 s33, s4
	s_cbranch_scc1 .Lsl8_out
	s_add_u32 s94, s34, 0x1da0000
	s_addc_u32 s95, s35, 0
	v_writelane_b32 v252, s90, 0
	s_add_u32 s4, s34, 0x7a0000
	s_addc_u32 s5, s35, 0
	v_writelane_b32 v252, s91, 1
	v_writelane_b32 v252, s4, 2
	v_lshrrev_b32_e32 v138, 8, v204
	v_and_b32_e32 v139, 0xff, v204
	v_writelane_b32 v252, s5, 3
	s_add_u32 s4, s34, 0x720000
	s_addc_u32 s5, s35, 0
	v_writelane_b32 v252, s4, 4
	v_mul_u32_u24_e32 v140, 0x12000, v138
	v_mov_b32_e32 v129, 0
	v_writelane_b32 v252, s5, 5
	s_add_u32 s4, s34, 0x520000
	s_addc_u32 s5, s35, 0
	s_add_u32 s90, s34, 0x4a0000
	s_addc_u32 s91, s35, 0
	s_add_u32 s96, s34, 0x440000
	s_addc_u32 s97, s35, 0
	s_add_u32 s16, s34, 0x28a0000
	s_addc_u32 s17, s35, 0
	s_add_u32 s18, s0, 0x120
	v_writelane_b32 v252, s4, 6
	s_addc_u32 s19, s1, 0
	s_movk_i32 s8, 0x104
	s_movk_i32 s9, 0xffe0
	s_movk_i32 s10, 0x6000
	s_movk_i32 s11, 0x400
	s_mov_b32 s12, 0xbfb8aa3b
	s_mov_b32 s13, 0x42ce8ed0
	s_mov_b32 s14, 0xc2b17218
	s_movk_i32 s15, 0x1800
	v_mov_b32_e32 v141, 0xfffffd40
	v_mov_b32_e32 v142, 0xb00000
	v_mov_b32_e32 v143, 0x580000
	v_mov_b32_e32 v144, 0x7f800000
	v_writelane_b32 v252, s5, 7
	s_branch .Lsl8_22

.Lsl8_out:
	s_cmp_gt_i32 s88, 8
	s_cbranch_scc1 .Lsb8_skip
	s_cmp_lt_i32 s89, 10
	s_cbranch_scc1 .Lsb8_skip
	s_waitcnt lgkmcnt(0)
	s_and_saveexec_b64 s[16:17], s[92:93]
	s_cbranch_execz .Lsb8_done
	v_mov_b32_e32 v0, 0x24008
	ds_read_b32 v1, v0
	buffer_inv sc1
	s_add_u32 s18, s34, 0xed10500
	s_addc_u32 s19, s35, 0
	v_mov_b32_e32 v0, 0
	s_mov_b32 s20, 0
	s_waitcnt lgkmcnt(0)

.LBB0_1201:
	s_or_b64 exec, exec, s[4:5]
	s_waitcnt lgkmcnt(0)
.LBB0_1202:
	s_cmp_lg_u32 s88, 0
	s_cbranch_scc1 .Lsl9_out
	s_cmp_lg_u32 s89, 18
	s_cbranch_scc1 .Lsl9_out
	s_load_dword s4, s[0:1], 0x120
	s_load_dwordx16 s[52:67], s[0:1], 0x0
	s_load_dwordx16 s[68:83], s[0:1], 0x80
	s_waitcnt lgkmcnt(0)
	s_lshl_b32 s4, s4, 1
	s_mul_i32 s5, s4, 10
	s_lshl_b32 s33, s2, 1
	s_add_i32 s33, s33, s5
	s_mov_b32 s5, 11
	s_mul_i32 s4, s4, s5
	s_min_u32 s4, s4, 0x15d0
	s_cmp_ge_i32 s33, s4
	s_cbranch_scc1 .Lsl9_out
	s_add_u32 s94, s34, 0x1da0000
	s_addc_u32 s95, s35, 0
	v_writelane_b32 v252, s90, 0
	s_add_u32 s4, s34, 0x7a0000
	s_addc_u32 s5, s35, 0
	v_writelane_b32 v252, s91, 1
	v_writelane_b32 v252, s4, 2
	v_lshrrev_b32_e32 v138, 8, v204
	v_and_b32_e32 v139, 0xff, v204
	v_writelane_b32 v252, s5, 3
	s_add_u32 s4, s34, 0x720000
	s_addc_u32 s5, s35, 0
	v_writelane_b32 v252, s4, 4
	v_mul_u32_u24_e32 v140, 0x12000, v138
	v_mov_b32_e32 v129, 0
	v_writelane_b32 v252, s5, 5
	s_add_u32 s4, s34, 0x520000
	s_addc_u32 s5, s35, 0
	s_add_u32 s90, s34, 0x4a0000
	s_addc_u32 s91, s35, 0
	s_add_u32 s96, s34, 0x440000
	s_addc_u32 s97, s35, 0
	s_add_u32 s16, s34, 0x28a0000
	s_addc_u32 s17, s35, 0
	s_add_u32 s18, s0, 0x120
	v_writelane_b32 v252, s4, 6
	s_addc_u32 s19, s1, 0
	s_movk_i32 s8, 0x104
	s_movk_i32 s9, 0xffe0
	s_movk_i32 s10, 0x6000
	s_movk_i32 s11, 0x400
	s_mov_b32 s12, 0xbfb8aa3b
	s_mov_b32 s13, 0x42ce8ed0
	s_mov_b32 s14, 0xc2b17218
	s_movk_i32 s15, 0x1800
	v_mov_b32_e32 v141, 0xfffffd40
	v_mov_b32_e32 v142, 0xb00000
	v_mov_b32_e32 v143, 0x580000
	v_mov_b32_e32 v144, 0x7f800000
	v_writelane_b32 v252, s5, 7
	s_branch .Lsl9_22

.Lsl9_out:
	s_cmp_gt_i32 s88, 9
	s_cbranch_scc1 .Lsb9_skip
	s_cmp_lt_i32 s89, 11
	s_cbranch_scc1 .Lsb9_skip
	s_waitcnt lgkmcnt(0)
	s_and_saveexec_b64 s[16:17], s[92:93]
	s_cbranch_execz .Lsb9_done
	v_mov_b32_e32 v0, 0x24008
	ds_read_b32 v1, v0
	buffer_inv sc1
	s_add_u32 s18, s34, 0xed10500
	s_addc_u32 s19, s35, 0
	v_mov_b32_e32 v0, 0
	s_mov_b32 s20, 0
	s_waitcnt lgkmcnt(0)
